# sample item P.V: 32 dwordx4 loads instead of 128 dword loads
# speedup vs baseline: 1.0026x; 1.0026x over previous
.LBB0_289:
	v_lshl_add_u64 v[22:23], v[20:21], 0, s[20:21]
	v_lshl_add_u64 v[34:35], v[18:19], 0, s[20:21]
	global_load_dword v36, v[22:23], off
	global_load_dword v38, v[22:23], off offset:256
	global_load_dword v40, v[22:23], off offset:512
	global_load_dword v42, v[22:23], off offset:768
	global_load_dword v44, v[22:23], off offset:1024
	global_load_dword v46, v[22:23], off offset:1280
	global_load_dword v48, v[22:23], off offset:1536
	global_load_dword v50, v[22:23], off offset:1792
	global_load_dword v37, v[34:35], off
	global_load_dword v39, v[34:35], off offset:256
	global_load_dword v41, v[34:35], off offset:512
	global_load_dword v43, v[34:35], off offset:768
	global_load_dword v45, v[34:35], off offset:1024
	global_load_dword v47, v[34:35], off offset:1280
	global_load_dword v49, v[34:35], off offset:1536
	global_load_dword v51, v[34:35], off offset:1792
	global_load_dword v52, v[22:23], off offset:2048
	global_load_dword v54, v[22:23], off offset:2304
	global_load_dword v56, v[22:23], off offset:2560
	global_load_dword v58, v[22:23], off offset:2816
	global_load_dword v60, v[22:23], off offset:3072
	global_load_dword v62, v[22:23], off offset:3328
	global_load_dword v64, v[22:23], off offset:3584
	global_load_dword v66, v[22:23], off offset:3840
	global_load_dword v53, v[34:35], off offset:2048
	global_load_dword v55, v[34:35], off offset:2304
	global_load_dword v57, v[34:35], off offset:2560
	global_load_dword v59, v[34:35], off offset:2816
	global_load_dword v61, v[34:35], off offset:3072
	global_load_dword v63, v[34:35], off offset:3328
	global_load_dword v65, v[34:35], off offset:3584
	global_load_dword v67, v[34:35], off offset:3840
	v_add_co_u32_e32 v22, vcc, s29, v22
	v_add_u32_e32 v11, 0xffffff84, v2
	s_nop 0
	v_addc_co_u32_e32 v23, vcc, 0, v23, vcc
	v_add_co_u32_e32 v34, vcc, s29, v34
	v_add_u32_e32 v99, 0xffffff88, v2
	s_nop 0
	v_addc_co_u32_e32 v35, vcc, 0, v35, vcc
	global_load_dword v68, v[22:23], off
	global_load_dword v70, v[22:23], off offset:256
	global_load_dword v72, v[22:23], off offset:512
	global_load_dword v74, v[22:23], off offset:768
	global_load_dword v76, v[22:23], off offset:1024
	global_load_dword v78, v[22:23], off offset:1280
	global_load_dword v80, v[22:23], off offset:1536
	global_load_dword v82, v[22:23], off offset:1792
	global_load_dword v69, v[34:35], off
	global_load_dword v71, v[34:35], off offset:256
	global_load_dword v73, v[34:35], off offset:512
	global_load_dword v75, v[34:35], off offset:768
	global_load_dword v77, v[34:35], off offset:1024
	global_load_dword v79, v[34:35], off offset:1280
	global_load_dword v81, v[34:35], off offset:1536
	global_load_dword v83, v[34:35], off offset:1792
	global_load_dword v84, v[22:23], off offset:2048
	global_load_dword v86, v[22:23], off offset:2304
	global_load_dword v88, v[22:23], off offset:2560
	global_load_dword v90, v[22:23], off offset:2816
	global_load_dword v92, v[22:23], off offset:3072
	global_load_dword v94, v[22:23], off offset:3328
	global_load_dword v96, v[22:23], off offset:3584
	s_nop 0
	global_load_dword v22, v[22:23], off offset:3840
	s_nop 0
	global_load_dword v85, v[34:35], off offset:2048
	global_load_dword v87, v[34:35], off offset:2304
	global_load_dword v89, v[34:35], off offset:2560
	global_load_dword v91, v[34:35], off offset:2816
	global_load_dword v93, v[34:35], off offset:3072
	global_load_dword v95, v[34:35], off offset:3328
	global_load_dword v97, v[34:35], off offset:3584
	global_load_dword v23, v[34:35], off offset:3840
	ds_bpermute_b32 v98, v11, v1
	v_add_u32_e32 v101, 0xffffff8c, v2
	ds_bpermute_b32 v100, v99, v1
	v_add_u32_e32 v103, 0xffffff90, v2
	ds_bpermute_b32 v102, v101, v1
	v_add_u32_e32 v105, 0xffffff94, v2
	ds_bpermute_b32 v104, v103, v1
	v_add_u32_e32 v107, 0xffffff98, v2
	ds_bpermute_b32 v106, v105, v1
	v_add_u32_e32 v109, 0xffffff9c, v2
	ds_bpermute_b32 v108, v107, v1
	v_add_u32_e32 v111, 0xffffffa0, v2
	ds_bpermute_b32 v110, v109, v1
	v_add_u32_e32 v113, 0xffffffa4, v2
	ds_bpermute_b32 v112, v111, v1
	v_add_u32_e32 v115, 0xffffffa8, v2
	ds_bpermute_b32 v114, v113, v1
	v_add_u32_e32 v117, 0xffffffac, v2
	ds_bpermute_b32 v116, v115, v1
	v_add_u32_e32 v119, 0xffffffb0, v2
	ds_bpermute_b32 v118, v117, v1
	v_add_u32_e32 v121, 0xffffffb4, v2
	ds_bpermute_b32 v120, v119, v1
	v_add_u32_e32 v123, 0xffffffb8, v2
	ds_bpermute_b32 v122, v121, v1
	v_add_u32_e32 v125, 0xffffffbc, v2
	ds_bpermute_b32 v124, v123, v1
	v_subrev_u32_e32 v127, 64, v2
	ds_bpermute_b32 v126, v125, v1
	v_subrev_u32_e32 v129, 60, v2
	ds_bpermute_b32 v128, v127, v1
	v_subrev_u32_e32 v131, 56, v2
	ds_bpermute_b32 v130, v129, v1
	v_subrev_u32_e32 v133, 52, v2
	ds_bpermute_b32 v132, v131, v1
	v_subrev_u32_e32 v35, 48, v2
	ds_bpermute_b32 v134, v133, v1
	v_subrev_u32_e32 v135, 44, v2
	ds_bpermute_b32 v136, v35, v1
	v_subrev_u32_e32 v137, 40, v2
	ds_bpermute_b32 v138, v135, v1
	v_subrev_u32_e32 v139, 36, v2
	ds_bpermute_b32 v140, v137, v1
	v_subrev_u32_e32 v141, 32, v2
	ds_bpermute_b32 v142, v139, v1
	s_waitcnt vmcnt(55) lgkmcnt(14)
	v_pk_fma_f32 v[16:17], v[36:37], v[98:99], v[16:17] op_sel_hi:[1,0,1]
	v_subrev_u32_e32 v143, 28, v2
	s_waitcnt vmcnt(54)
	v_pk_fma_f32 v[16:17], v[38:39], v[100:101], v[16:17] op_sel_hi:[1,0,1]
	ds_bpermute_b32 v146, v141, v1
	s_waitcnt vmcnt(53)
	v_pk_fma_f32 v[16:17], v[40:41], v[102:103], v[16:17] op_sel_hi:[1,0,1]
	v_subrev_u32_e32 v145, 24, v2
	s_waitcnt vmcnt(52)
	v_pk_fma_f32 v[16:17], v[42:43], v[104:105], v[16:17] op_sel_hi:[1,0,1]
	ds_bpermute_b32 v148, v143, v1
	s_waitcnt vmcnt(51)
	v_pk_fma_f32 v[16:17], v[44:45], v[106:107], v[16:17] op_sel_hi:[1,0,1]
	v_subrev_u32_e32 v147, 20, v2
	s_waitcnt vmcnt(50)
	v_pk_fma_f32 v[16:17], v[46:47], v[108:109], v[16:17] op_sel_hi:[1,0,1]
	ds_bpermute_b32 v150, v145, v1
	s_waitcnt vmcnt(49)
	v_pk_fma_f32 v[16:17], v[48:49], v[110:111], v[16:17] op_sel_hi:[1,0,1]
	v_add_u32_e32 v149, -16, v2
	s_waitcnt vmcnt(48)
	v_pk_fma_f32 v[16:17], v[50:51], v[112:113], v[16:17] op_sel_hi:[1,0,1]
	ds_bpermute_b32 v152, v147, v1
	s_waitcnt vmcnt(39)
	v_pk_fma_f32 v[16:17], v[52:53], v[114:115], v[16:17] op_sel_hi:[1,0,1]
	v_add_u32_e32 v151, -12, v2
	s_waitcnt vmcnt(38) lgkmcnt(14)
	v_pk_fma_f32 v[16:17], v[54:55], v[116:117], v[16:17] op_sel_hi:[1,0,1]
	ds_bpermute_b32 v154, v149, v1
	s_waitcnt vmcnt(37)
	v_pk_fma_f32 v[16:17], v[56:57], v[118:119], v[16:17] op_sel_hi:[1,0,1]
	v_add_u32_e32 v153, -8, v2
	s_waitcnt vmcnt(36)
	v_pk_fma_f32 v[16:17], v[58:59], v[120:121], v[16:17] op_sel_hi:[1,0,1]
	ds_bpermute_b32 v156, v151, v1
	s_waitcnt vmcnt(35)
	v_pk_fma_f32 v[16:17], v[60:61], v[122:123], v[16:17] op_sel_hi:[1,0,1]
	v_add_u32_e32 v155, -4, v2
	s_waitcnt vmcnt(34) lgkmcnt(14)
	v_pk_fma_f32 v[16:17], v[62:63], v[124:125], v[16:17] op_sel_hi:[1,0,1]
	ds_bpermute_b32 v158, v153, v1
	s_waitcnt vmcnt(33)
	v_pk_fma_f32 v[16:17], v[64:65], v[126:127], v[16:17] op_sel_hi:[1,0,1]
	ds_bpermute_b32 v160, v155, v1
	s_waitcnt vmcnt(32) lgkmcnt(14)
	v_pk_fma_f32 v[16:17], v[66:67], v[128:129], v[16:17] op_sel_hi:[1,0,1]
	ds_bpermute_b32 v34, v2, v1
	s_waitcnt vmcnt(23)
	v_pk_fma_f32 v[16:17], v[68:69], v[130:131], v[16:17] op_sel_hi:[1,0,1]
	s_add_u32 s20, s20, 0x2000
	s_waitcnt vmcnt(22) lgkmcnt(14)
	v_pk_fma_f32 v[16:17], v[70:71], v[132:133], v[16:17] op_sel_hi:[1,0,1]
	s_addc_u32 s21, s21, 0
	s_waitcnt vmcnt(21) lgkmcnt(13)
	v_pk_fma_f32 v[16:17], v[72:73], v[134:135], v[16:17] op_sel_hi:[1,0,1]
	v_add_u32_e32 v2, 0x80, v2
	s_waitcnt vmcnt(20) lgkmcnt(12)
	v_pk_fma_f32 v[16:17], v[74:75], v[136:137], v[16:17] op_sel_hi:[1,0,1]
	s_cmpk_eq_i32 s20, 0x4000
	s_waitcnt vmcnt(19) lgkmcnt(11)
	v_pk_fma_f32 v[16:17], v[76:77], v[138:139], v[16:17] op_sel_hi:[1,0,1]
	s_waitcnt vmcnt(18) lgkmcnt(10)
	v_pk_fma_f32 v[16:17], v[78:79], v[140:141], v[16:17] op_sel_hi:[1,0,1]
	s_waitcnt vmcnt(17) lgkmcnt(9)
	v_pk_fma_f32 v[16:17], v[80:81], v[142:143], v[16:17] op_sel_hi:[1,0,1]
	s_waitcnt vmcnt(16) lgkmcnt(8)
	v_pk_fma_f32 v[16:17], v[82:83], v[146:147], v[16:17] op_sel_hi:[1,0,1]
	s_waitcnt vmcnt(7) lgkmcnt(7)
	v_pk_fma_f32 v[16:17], v[84:85], v[148:149], v[16:17] op_sel_hi:[1,0,1]
	s_waitcnt vmcnt(6) lgkmcnt(6)
	v_pk_fma_f32 v[16:17], v[86:87], v[150:151], v[16:17] op_sel_hi:[1,0,1]
	s_waitcnt vmcnt(5) lgkmcnt(5)
	v_pk_fma_f32 v[16:17], v[88:89], v[152:153], v[16:17] op_sel_hi:[1,0,1]
	s_waitcnt vmcnt(4) lgkmcnt(4)
	v_pk_fma_f32 v[16:17], v[90:91], v[154:155], v[16:17] op_sel_hi:[1,0,1]
	s_waitcnt vmcnt(3) lgkmcnt(3)
	v_pk_fma_f32 v[16:17], v[92:93], v[156:157], v[16:17] op_sel_hi:[1,0,1]
	s_waitcnt vmcnt(2) lgkmcnt(2)
	v_pk_fma_f32 v[16:17], v[94:95], v[158:159], v[16:17] op_sel_hi:[1,0,1]
	s_waitcnt vmcnt(1) lgkmcnt(1)
	v_pk_fma_f32 v[16:17], v[96:97], v[160:161], v[16:17] op_sel_hi:[1,0,1]
	s_waitcnt vmcnt(0) lgkmcnt(0)
	v_pk_fma_f32 v[16:17], v[22:23], v[34:35], v[16:17] op_sel_hi:[1,0,1]
	s_cbranch_scc0 .LBB0_289
	v_readlane_b32 s84, v254, 23
	v_lshlrev_b32_e32 v2, 2, v12
	v_readlane_b32 s98, v254, 37
	v_readlane_b32 s99, v254, 38
	v_mul_f32_e32 v11, 0xbfb8aa3b, v16
	v_exp_f32_e32 v11, v11
	s_lshl_b32 s51, s51, 6
	v_readlane_b32 s52, v254, 7
	s_lshr_b32 s2, s50, 2
	global_load_dword v18, v2, s[98:99]
	s_lshl_b64 s[20:21], s[18:19], 12
	s_and_b32 s51, s51, 0x300
	v_readlane_b32 s62, v254, 17
	v_readlane_b32 s53, v254, 8
	v_readlane_b32 s63, v254, 18
	s_add_u32 s52, s62, s20
	v_mul_f32_e32 v19, 0xbfb8aa3b, v17
	v_lshlrev_b32_e32 v20, 1, v0
	s_addc_u32 s53, s63, s21
	v_add_f32_e32 v11, 1.0, v11
	v_exp_f32_e32 v21, v19
	v_lshl_or_b32 v19, s2, 7, v20
	global_load_dword v20, v2, s[52:53]
	v_rcp_f32_e32 v22, v11
	v_add_co_u32_e32 v16, vcc, s29, v14
	v_add_f32_e32 v21, 1.0, v21
	s_nop 0
	v_addc_co_u32_e32 v17, vcc, 0, v15, vcc
	v_mul_f32_e32 v22, 0xc1000000, v22
	v_rcp_f32_e32 v21, v21
	s_add_u32 s20, s80, s20
	s_addc_u32 s21, s81, s21
	s_lshl_b32 s18, s18, 7
	v_readlane_b32 s56, v254, 11
	v_readlane_b32 s57, v254, 12
	s_lshl_b32 s2, s2, 8
	v_mov_b32_e32 v126, s24
	v_readlane_b32 s85, v254, 24
	s_ashr_i32 s19, s18, 31
	v_readlane_b32 s86, v254, 25
	v_readlane_b32 s87, v254, 26
	v_readlane_b32 s88, v254, 27
	v_readlane_b32 s89, v254, 28
	v_readlane_b32 s90, v254, 29
	v_readlane_b32 s91, v254, 30
	v_readlane_b32 s92, v254, 31
	v_readlane_b32 s93, v254, 32
	v_readlane_b32 s94, v254, 33
	v_readlane_b32 s95, v254, 34
	v_readlane_b32 s96, v254, 35
	v_readlane_b32 s97, v254, 36
	v_readlane_b32 s54, v254, 9
	v_readlane_b32 s55, v254, 10
	v_readlane_b32 s58, v254, 13
	v_readlane_b32 s59, v254, 14
	v_readlane_b32 s60, v254, 15
	v_readlane_b32 s61, v254, 16
	v_readlane_b32 s64, v254, 19
	v_readlane_b32 s65, v254, 20
	v_readlane_b32 s66, v254, 21
	v_readlane_b32 s67, v254, 22
	s_waitcnt vmcnt(1)
	v_mul_f32_e32 v11, 0xbfb8aa3b, v18
	v_fma_f32 v23, v18, s33, -v11
	v_rndne_f32_e32 v34, v11
	v_fmac_f32_e32 v23, 0xb2a5705f, v18
	v_sub_f32_e32 v11, v11, v34
	v_add_f32_e32 v11, v11, v23
	v_cvt_i32_f32_e32 v34, v34
	v_exp_f32_e32 v23, v11
	global_load_ushort v11, v[16:17], off offset:1024
	global_load_ushort v35, v19, s[0:1] offset:2560
	global_load_ushort v80, v19, s[0:1] offset:2048
	global_load_ushort v36, v[14:15], off
	v_cmp_nlt_f32_e32 vcc, s34, v18
	v_ldexp_f32 v19, v23, v34
	s_nop 0
	v_cndmask_b32_e32 v19, 0, v19, vcc
	v_cmp_ngt_f32_e32 vcc, s35, v18
	s_nop 1
	v_cndmask_b32_e32 v23, v33, v19, vcc
	v_add_f32_e32 v34, 1.0, v23
	v_add_f32_e32 v37, -1.0, v34
	v_frexp_mant_f32_e32 v38, v34
	v_cvt_f64_f32_e32 v[18:19], v34
	v_sub_f32_e32 v39, v37, v34
	v_frexp_exp_i32_f64_e32 v18, v[18:19]
	v_cmp_gt_f32_e32 vcc, s37, v38
	v_sub_f32_e32 v37, v23, v37
	v_add_f32_e32 v19, 1.0, v39
	v_subbrev_co_u32_e32 v18, vcc, 0, v18, vcc
	v_add_f32_e32 v19, v37, v19
	v_sub_u32_e32 v37, 0, v18
	v_cvt_f32_i32_e32 v18, v18
	v_ldexp_f32 v34, v34, v37
	v_ldexp_f32 v19, v19, v37
	v_add_f32_e32 v37, -1.0, v34
	v_add_f32_e32 v38, 1.0, v34
	v_add_f32_e32 v39, 1.0, v37
	v_add_f32_e32 v40, -1.0, v38
	v_sub_f32_e32 v39, v34, v39
	v_sub_f32_e32 v34, v34, v40
	v_mul_f32_e32 v40, 0x3f317218, v18
	v_add_f32_e32 v39, v19, v39
	v_add_f32_e32 v19, v19, v34
	v_fma_f32 v34, v18, s38, -v40
	v_add_f32_e32 v41, v37, v39
	v_add_f32_e32 v42, v38, v19
	v_fmac_f32_e32 v34, 0xb102e308, v18
	v_sub_f32_e32 v18, v37, v41
	v_sub_f32_e32 v37, v38, v42
	v_rcp_f32_e32 v38, v42
	v_add_f32_e32 v43, v40, v34
	v_add_f32_e32 v19, v19, v37
	v_sub_f32_e32 v37, v43, v40
	v_sub_f32_e32 v34, v34, v37
	v_mul_f32_e32 v37, v41, v38
	v_add_f32_e32 v18, v39, v18
	v_mul_f32_e32 v39, v42, v37
	v_fma_f32 v40, v37, v42, -v39
	v_fmac_f32_e32 v40, v37, v19
	v_add_f32_e32 v44, v39, v40
	v_sub_f32_e32 v45, v41, v44
	v_sub_f32_e32 v39, v44, v39
	v_sub_f32_e32 v41, v41, v45
	v_sub_f32_e32 v39, v39, v40
	v_sub_f32_e32 v40, v41, v44
	v_add_f32_e32 v18, v18, v40
	v_add_f32_e32 v18, v39, v18
	v_add_f32_e32 v39, v45, v18
	v_mul_f32_e32 v40, v38, v39
	v_sub_f32_e32 v41, v45, v39
	v_mul_f32_e32 v44, v42, v40
	v_add_f32_e32 v18, v18, v41
	v_add_f32_e32 v41, v37, v40
	v_fma_f32 v42, v40, v42, -v44
	v_sub_f32_e32 v37, v41, v37
	v_fmac_f32_e32 v42, v40, v19
	v_sub_f32_e32 v19, v40, v37
	v_add_f32_e32 v37, v44, v42
	v_sub_f32_e32 v40, v37, v44
	v_sub_f32_e32 v44, v39, v37
	v_sub_f32_e32 v39, v39, v44
	v_sub_f32_e32 v37, v39, v37
	v_sub_f32_e32 v40, v40, v42
	v_add_f32_e32 v18, v18, v37
	v_add_f32_e32 v18, v40, v18
	v_add_f32_e32 v18, v44, v18
	v_mul_f32_e32 v18, v38, v18
	v_add_f32_e32 v18, v19, v18
	v_add_f32_e32 v19, v41, v18
	v_mul_f32_e32 v37, v19, v19
	v_fmamk_f32 v40, v37, 0x3e9b6dac, v31
	v_sub_f32_e32 v38, v19, v41
	v_ldexp_f32 v39, v19, 1
	v_mul_f32_e32 v19, v19, v37
	v_fmaak_f32 v37, v37, v40, 0x3f2aaada
	v_mul_f32_e32 v19, v19, v37
	v_add_f32_e32 v37, v39, v19
	v_sub_f32_e32 v18, v18, v38
	v_sub_f32_e32 v38, v37, v39
	v_ldexp_f32 v18, v18, 1
	v_sub_f32_e32 v19, v19, v38
	v_add_f32_e32 v18, v18, v19
	v_add_f32_e32 v19, v37, v18
	v_sub_f32_e32 v37, v19, v37
	v_add_f32_e32 v38, v43, v19
	v_sub_f32_e32 v18, v18, v37
	v_sub_f32_e32 v37, v38, v43
	v_sub_f32_e32 v39, v38, v37
	v_sub_f32_e32 v19, v19, v37
	v_add_f32_e32 v37, v34, v18
	v_sub_f32_e32 v39, v43, v39
	v_sub_f32_e32 v40, v37, v34
	v_add_f32_e32 v19, v19, v39
	v_sub_f32_e32 v39, v37, v40
	v_sub_f32_e32 v18, v18, v40
	v_sub_f32_e32 v34, v34, v39
	v_add_f32_e32 v19, v37, v19
	v_add_f32_e32 v18, v18, v34
	v_add_f32_e32 v34, v38, v19
	v_sub_f32_e32 v37, v34, v38
	v_sub_f32_e32 v19, v19, v37
	v_add_f32_e32 v18, v18, v19
	v_add_f32_e32 v18, v34, v18
	v_cmp_neq_f32_e32 vcc, s36, v23
	s_nop 1
	v_cndmask_b32_e32 v18, v33, v18, vcc
	v_cmp_lt_f32_e64 vcc, |v23|, s39
	s_nop 1
	v_cndmask_b32_e32 v18, v18, v23, vcc
	v_mul_f32_e32 v18, v22, v18
	v_add_f32_e32 v19, v18, v18
	v_mul_f32_e32 v19, 0x3fb8aa3b, v19
	v_exp_f32_e32 v19, v19
	v_mul_f32_e32 v18, 0x3fb8aa3b, v18
	v_exp_f32_e32 v18, v18
	v_sub_f32_e32 v19, 1.0, v19
	v_max_f32_e32 v19, 0, v19
	v_mul_f32_e32 v22, 0x4f800000, v19
	v_cmp_gt_f32_e32 vcc, s40, v19
	s_nop 1
	v_cndmask_b32_e32 v19, v19, v22, vcc
	v_sqrt_f32_e32 v22, v19
	s_nop 0
	v_add_u32_e32 v23, -1, v22
	v_add_u32_e32 v34, 1, v22
	v_fma_f32 v37, -v23, v22, v19
	v_fma_f32 v38, -v34, v22, v19
	v_cmp_ge_f32_e64 s[0:1], 0, v37
	s_nop 1
	v_cndmask_b32_e64 v22, v22, v23, s[0:1]
	v_cmp_lt_f32_e64 s[0:1], 0, v38
	s_nop 1
	v_cndmask_b32_e64 v22, v22, v34, s[0:1]
	v_mul_f32_e32 v23, 0x37800000, v22
	v_cndmask_b32_e32 v22, v22, v23, vcc
	v_cmp_class_f32_e32 vcc, v19, v32
	s_lshl_b32 s0, s50, 2
	s_nop 0
	v_cndmask_b32_e32 v19, v22, v19, vcc
	v_mul_f32_e32 v19, v21, v19
	v_mul_f32_e32 v34, v1, v19
	s_waitcnt vmcnt(4)
	v_fmac_f32_e32 v34, v20, v18
	v_lshl_add_u64 v[18:19], s[20:21], 0, v[2:3]
	v_add_co_u32_e32 v18, vcc, s41, v18
	s_waitcnt vmcnt(0)
	v_lshlrev_b32_e32 v2, 16, v36
	v_addc_co_u32_e32 v19, vcc, 0, v19, vcc
	global_store_dword v[18:19], v34, off
	v_or_b32_e32 v18, s18, v0
	v_ashrrev_i32_e32 v19, 31, v18
	v_lshlrev_b64 v[18:19], 10, v[18:19]
	v_lshl_add_u64 v[18:19], s[56:57], 0, v[18:19]
	v_lshl_add_u64 v[18:19], v[18:19], 0, s[2:3]
	ds_write_b32 v13, v2
	s_waitcnt lgkmcnt(0)
	v_add_co_u32_e32 v20, vcc, s42, v18
	global_load_dwordx4 v[36:39], v[18:19], off
	s_nop 0
	v_addc_co_u32_e32 v21, vcc, 0, v19, vcc
	global_load_dwordx4 v[40:43], v[20:21], off
	global_load_dwordx4 v[44:47], v[18:19], off offset:16
	v_lshl_add_u64 v[22:23], v[18:19], 0, s[8:9]
	global_load_dwordx4 v[48:51], v[22:23], off offset:16
	global_load_dwordx4 v[52:55], v[18:19], off offset:32
	global_load_dwordx4 v[56:59], v[22:23], off offset:32
	global_load_dwordx4 v[60:63], v[18:19], off offset:48
	global_load_dwordx4 v[64:67], v[22:23], off offset:48
	global_load_dwordx4 v[68:71], v[18:19], off offset:64
	global_load_dwordx4 v[72:75], v[20:21], off offset:64
	global_load_dwordx4 v[76:79], v[18:19], off offset:80
	v_lshl_add_u64 v[112:113], v[18:19], 0, s[10:11]
	v_lshlrev_b32_e32 v1, 16, v80
	ds_read_b128 v[80:83], v126
	ds_read_b128 v[84:87], v126 offset:16
	ds_read_b128 v[88:91], v126 offset:32
	ds_read_b128 v[92:95], v126 offset:48
	global_load_dwordx4 v[96:99], v[112:113], off offset:16
	global_load_dwordx4 v[100:103], v[18:19], off offset:112
	global_load_dwordx4 v[104:107], v[18:19], off offset:96
	global_load_dwordx4 v[108:111], v[112:113], off offset:48
	s_nop 0
	global_load_dwordx4 v[112:115], v[112:113], off offset:32
	s_nop 0
	global_load_dwordx4 v[116:119], v[18:19], off offset:144
	global_load_dwordx4 v[120:123], v[18:19], off offset:128
	v_lshl_add_u64 v[124:125], v[18:19], 0, s[12:13]
	v_lshl_add_u64 v[22:23], v[18:19], 0, s[14:15]
	s_waitcnt vmcnt(14) lgkmcnt(2)
	v_mul_f32_e32 v49, v85, v49
	v_mul_f32_e32 v51, v87, v51
	v_mul_f32_e32 v37, v81, v37
	v_mul_f32_e32 v39, v83, v39
	v_mul_f32_e32 v41, v81, v41
	v_mul_f32_e32 v43, v83, v43
	v_mul_f32_e32 v45, v85, v45
	v_mul_f32_e32 v47, v87, v47
	v_fmac_f32_e32 v37, v80, v36
	v_fmac_f32_e32 v39, v82, v38
	v_fmac_f32_e32 v41, v80, v40
	v_fmac_f32_e32 v43, v82, v42
	s_waitcnt vmcnt(13) lgkmcnt(1)
	v_mul_f32_e32 v53, v89, v53
	v_mul_f32_e32 v55, v91, v55
	s_waitcnt vmcnt(12)
	v_mul_f32_e32 v57, v89, v57
	v_mul_f32_e32 v59, v91, v59
	v_fmac_f32_e32 v45, v84, v44
	v_fmac_f32_e32 v47, v86, v46
	v_fmac_f32_e32 v49, v84, v48
	v_fmac_f32_e32 v51, v86, v50
	v_add_f32_e32 v36, v37, v39
	v_add_f32_e32 v37, v41, v43
	v_fmac_f32_e32 v53, v88, v52
	v_fmac_f32_e32 v55, v90, v54
	v_fmac_f32_e32 v57, v88, v56
	v_fmac_f32_e32 v59, v90, v58
	v_add_f32_e32 v38, v45, v47
	v_add_f32_e32 v39, v49, v51
	v_add_f32_e32 v36, 0, v36
	v_add_f32_e32 v37, 0, v37
	s_waitcnt vmcnt(11) lgkmcnt(0)
	v_mul_f32_e32 v61, v93, v61
	v_mul_f32_e32 v63, v95, v63
	v_add_f32_e32 v40, v53, v55
	v_add_f32_e32 v41, v57, v59
	v_add_f32_e32 v36, v36, v38
	v_add_f32_e32 v37, v37, v39
	v_fmac_f32_e32 v61, v92, v60
	v_fmac_f32_e32 v63, v94, v62
	v_add_f32_e32 v40, v36, v40
	v_add_f32_e32 v44, v37, v41
	global_load_dwordx4 v[36:39], v[20:21], off offset:128
	v_add_f32_e32 v41, v61, v63
	v_add_f32_e32 v56, v40, v41
	ds_read_b128 v[40:43], v126 offset:64
	s_waitcnt vmcnt(11)
	v_mul_f32_e32 v45, v93, v65
	v_mul_f32_e32 v46, v95, v67
	v_fmac_f32_e32 v45, v92, v64
	v_fmac_f32_e32 v46, v94, v66
	v_add_f32_e32 v45, v45, v46
	v_add_f32_e32 v64, v44, v45
	ds_read_b128 v[44:47], v126 offset:80
	s_waitcnt vmcnt(10) lgkmcnt(1)
	v_mul_f32_e32 v57, v41, v69
	global_load_dwordx4 v[48:51], v[124:125], off offset:32
	global_load_dwordx4 v[52:55], v[124:125], off offset:16
	s_waitcnt vmcnt(11)
	v_mul_f32_e32 v41, v41, v73
	v_fmac_f32_e32 v57, v40, v68
	v_mul_f32_e32 v58, v43, v71
	v_fmac_f32_e32 v41, v40, v72
	v_mul_f32_e32 v40, v43, v75
	v_fmac_f32_e32 v58, v42, v70
	v_fmac_f32_e32 v40, v42, v74
	v_add_f32_e32 v57, v57, v58
	v_add_f32_e32 v40, v41, v40
	v_add_f32_e32 v65, v56, v57
	global_load_dwordx4 v[56:59], v[18:19], off offset:176
	global_load_dwordx4 v[60:63], v[18:19], off offset:160
	v_add_f32_e32 v64, v64, v40
	s_waitcnt vmcnt(12) lgkmcnt(0)
	v_mul_f32_e32 v40, v45, v77
	v_mul_f32_e32 v41, v47, v79
	v_fmac_f32_e32 v40, v44, v76
	v_fmac_f32_e32 v41, v46, v78
	v_add_f32_e32 v40, v40, v41
	v_add_f32_e32 v76, v65, v40
	ds_read_b128 v[40:43], v126 offset:96
	s_waitcnt vmcnt(11)
	v_mul_f32_e32 v45, v45, v97
	v_fmac_f32_e32 v45, v44, v96
	v_mul_f32_e32 v44, v47, v99
	v_fmac_f32_e32 v44, v46, v98
	v_add_f32_e32 v44, v45, v44
	v_add_f32_e32 v77, v64, v44
	global_load_dwordx4 v[44:47], v[124:125], off offset:48
	ds_read_b128 v[64:67], v126 offset:112
	s_waitcnt vmcnt(10) lgkmcnt(1)
	v_mul_f32_e32 v68, v41, v105
	v_mul_f32_e32 v69, v43, v107
	v_fmac_f32_e32 v68, v40, v104
	v_fmac_f32_e32 v69, v42, v106
	v_add_f32_e32 v78, v68, v69
	v_add_f32_e32 v76, v76, v78
	s_waitcnt vmcnt(8)
	v_mul_f32_e32 v78, v41, v113
	v_mul_f32_e32 v79, v43, v115
	global_load_dwordx4 v[68:71], v[18:19], off offset:208
	global_load_dwordx4 v[72:75], v[18:19], off offset:192
	v_fmac_f32_e32 v78, v40, v112
	v_fmac_f32_e32 v79, v42, v114
	global_load_dwordx4 v[40:43], v[20:21], off offset:192
	v_add_f32_e32 v20, v78, v79
	v_add_f32_e32 v20, v77, v20
	s_waitcnt lgkmcnt(0)
	v_mul_f32_e32 v21, v65, v101
	v_mul_f32_e32 v77, v67, v103
	v_fmac_f32_e32 v21, v64, v100
	v_fmac_f32_e32 v77, v66, v102
	v_add_f32_e32 v21, v21, v77
	v_add_f32_e32 v21, v76, v21
	v_mul_f32_e32 v76, v65, v109
	v_mul_f32_e32 v77, v67, v111
	v_fmac_f32_e32 v76, v64, v108
	v_fmac_f32_e32 v77, v66, v110
	ds_read_b128 v[64:67], v126 offset:128
	v_add_f32_e32 v80, v76, v77
	global_load_dwordx4 v[76:79], v[22:23], off offset:16
	v_add_f32_e32 v20, v20, v80
	ds_read_b128 v[80:83], v126 offset:144
	global_load_dwordx4 v[84:87], v[18:19], off offset:240
	global_load_dwordx4 v[88:91], v[18:19], off offset:224
	s_waitcnt vmcnt(12) lgkmcnt(1)
	v_mul_f32_e32 v92, v65, v121
	v_mul_f32_e32 v93, v67, v123
	v_fmac_f32_e32 v92, v64, v120
	v_fmac_f32_e32 v93, v66, v122
	v_add_f32_e32 v18, v92, v93
	global_load_dwordx4 v[92:95], v[22:23], off offset:48
	global_load_dwordx4 v[96:99], v[22:23], off offset:32
	v_add_f32_e32 v18, v21, v18
	s_waitcnt vmcnt(13)
	v_mul_f32_e32 v19, v65, v37
	v_mul_f32_e32 v21, v67, v39
	v_fmac_f32_e32 v19, v64, v36
	v_fmac_f32_e32 v21, v66, v38
	v_add_f32_e32 v19, v19, v21
	v_add_f32_e32 v22, v20, v19
	s_waitcnt lgkmcnt(0)
	v_mul_f32_e32 v19, v81, v117
	v_mul_f32_e32 v20, v83, v119
	v_fmac_f32_e32 v19, v80, v116
	v_fmac_f32_e32 v20, v82, v118
	v_add_f32_e32 v19, v19, v20
	v_add_f32_e32 v23, v18, v19
	ds_read_b128 v[18:21], v126 offset:160
	s_waitcnt vmcnt(11)
	v_mul_f32_e32 v36, v81, v53
	v_mul_f32_e32 v37, v83, v55
	v_fmac_f32_e32 v36, v80, v52
	v_fmac_f32_e32 v37, v82, v54
	v_add_f32_e32 v36, v36, v37
	v_add_f32_e32 v22, v22, v36
	ds_read_b128 v[36:39], v126 offset:176
	s_waitcnt vmcnt(9) lgkmcnt(1)
	v_mul_f32_e32 v52, v19, v61
	v_mul_f32_e32 v19, v19, v49
	v_fmac_f32_e32 v52, v18, v60
	v_fmac_f32_e32 v19, v18, v48
	v_mul_f32_e32 v18, v21, v51
	v_fmac_f32_e32 v18, v20, v50
	v_mul_f32_e32 v53, v21, v63
	v_add_f32_e32 v18, v19, v18
	v_fmac_f32_e32 v53, v20, v62
	v_add_f32_e32 v22, v22, v18
	s_waitcnt lgkmcnt(0)
	v_mul_f32_e32 v18, v37, v57
	v_mul_f32_e32 v19, v39, v59
	v_add_f32_e32 v52, v52, v53
	v_fmac_f32_e32 v18, v36, v56
	v_fmac_f32_e32 v19, v38, v58
	v_add_f32_e32 v23, v23, v52
	v_add_f32_e32 v18, v18, v19
	v_add_f32_e32 v23, v23, v18
	ds_read_b128 v[18:21], v126 offset:192
	s_waitcnt vmcnt(8)
	v_mul_f32_e32 v37, v37, v45
	v_fmac_f32_e32 v37, v36, v44
	v_mul_f32_e32 v36, v39, v47
	v_fmac_f32_e32 v36, v38, v46
	v_add_f32_e32 v36, v37, v36
	v_add_f32_e32 v22, v22, v36
	ds_read_b128 v[36:39], v126 offset:208
	s_waitcnt vmcnt(6) lgkmcnt(1)
	v_mul_f32_e32 v44, v19, v73
	v_fmac_f32_e32 v44, v18, v72
	s_waitcnt vmcnt(5)
	v_mul_f32_e32 v19, v19, v41
	v_mul_f32_e32 v45, v21, v75
	v_fmac_f32_e32 v19, v18, v40
	v_mul_f32_e32 v18, v21, v43
	v_fmac_f32_e32 v45, v20, v74
	v_fmac_f32_e32 v18, v20, v42
	v_mov_b32_e32 v20, s0
	global_load_dword v20, v20, s[84:85]
	v_add_f32_e32 v18, v19, v18
	s_waitcnt lgkmcnt(0)
	v_mul_f32_e32 v19, v37, v69
	v_mul_f32_e32 v21, v39, v71
	ds_read_b128 v[40:43], v126 offset:224
	v_fmac_f32_e32 v19, v36, v68
	v_fmac_f32_e32 v21, v38, v70
	v_add_f32_e32 v18, v22, v18
	v_add_f32_e32 v19, v19, v21
	s_waitcnt vmcnt(5)
	v_mul_f32_e32 v21, v37, v77
	v_mul_f32_e32 v22, v39, v79
	v_fmac_f32_e32 v21, v36, v76
	v_fmac_f32_e32 v22, v38, v78
	v_add_f32_e32 v21, v21, v22
	v_add_f32_e32 v44, v44, v45
	v_add_f32_e32 v18, v18, v21
	ds_read_b128 v[36:39], v126 offset:240
	s_waitcnt vmcnt(3) lgkmcnt(1)
	v_mul_f32_e32 v21, v41, v89
	v_mul_f32_e32 v22, v43, v91
	v_add_f32_e32 v23, v23, v44
	v_fmac_f32_e32 v21, v40, v88
	v_fmac_f32_e32 v22, v42, v90
	v_add_f32_e32 v19, v23, v19
	v_add_f32_e32 v21, v21, v22
	v_add_f32_e32 v19, v19, v21
	s_waitcnt vmcnt(1)
	v_mul_f32_e32 v21, v41, v97
	v_mul_f32_e32 v22, v43, v99
	v_fmac_f32_e32 v21, v40, v96
	v_fmac_f32_e32 v22, v42, v98
	v_add_f32_e32 v21, v21, v22
	v_add_f32_e32 v18, v18, v21
	s_waitcnt lgkmcnt(0)
	v_mul_f32_e32 v21, v37, v85
	v_mul_f32_e32 v22, v39, v87
	v_fmac_f32_e32 v21, v36, v84
	v_fmac_f32_e32 v22, v38, v86
	v_add_f32_e32 v21, v21, v22
	v_add_f32_e32 v19, v19, v21
	v_mul_f32_e32 v21, v37, v93
	v_mul_f32_e32 v22, v39, v95
	v_fmac_f32_e32 v21, v36, v92
	v_fmac_f32_e32 v22, v38, v94
	v_add_f32_e32 v21, v21, v22
	v_add_f32_e32 v18, v18, v21
	v_mul_f32_e32 v22, 0x3e000000, v19
	v_mul_f32_e32 v23, 0x3e000000, v18
	v_max_f32_e32 v22, v22, v23
	ds_bpermute_b32 v23, v24, v22
	v_mul_f32_e32 v21, v1, v2
	ds_bpermute_b32 v21, v24, v21
	s_lshl_b64 s[0:1], s[18:19], 10
	s_or_b32 s0, s0, s51
	s_waitcnt lgkmcnt(1)
	v_max_f32_e32 v23, v23, v23
	v_max_f32_e32 v22, v22, v23
	s_waitcnt lgkmcnt(0)
	v_fmac_f32_e32 v21, v1, v2
	ds_bpermute_b32 v23, v25, v22
	ds_bpermute_b32 v2, v25, v21
	s_movk_i32 s19, 0xfe00
	s_waitcnt lgkmcnt(1)
	v_max_f32_e32 v23, v23, v23
	s_waitcnt lgkmcnt(0)
	v_add_f32_e32 v2, v21, v2
	v_max_f32_e32 v22, v22, v23
	ds_bpermute_b32 v21, v26, v2
	ds_bpermute_b32 v23, v26, v22
	s_waitcnt lgkmcnt(1)
	v_add_f32_e32 v2, v2, v21
	s_waitcnt lgkmcnt(0)
	v_max_f32_e32 v23, v23, v23
	ds_bpermute_b32 v21, v27, v2
	v_max_f32_e32 v22, v22, v23
	ds_bpermute_b32 v23, v27, v22
	s_waitcnt lgkmcnt(1)
	v_add_f32_e32 v2, v2, v21
	ds_bpermute_b32 v21, v28, v2
	s_waitcnt lgkmcnt(1)
	v_max_f32_e32 v23, v23, v23
	v_max_f32_e32 v22, v22, v23
	ds_bpermute_b32 v23, v28, v22
	s_waitcnt lgkmcnt(1)
	v_add_f32_e32 v2, v2, v21
	ds_bpermute_b32 v21, v29, v2
	s_waitcnt vmcnt(0)
	v_max_f32_e32 v36, v20, v20
	s_waitcnt lgkmcnt(1)
	v_max_f32_e32 v23, v23, v23
	v_max_f32_e32 v22, v22, v23
	ds_bpermute_b32 v23, v29, v22
	s_waitcnt lgkmcnt(1)
	v_add_f32_e32 v21, v2, v21
	v_mul_f32_e32 v2, 0x3e000000, v21
	v_max_f32_e32 v2, v2, v36
	s_waitcnt lgkmcnt(0)
	v_max3_f32 v22, v22, v23, v2
	v_fma_f32 v2, v19, s43, -v22
	v_mul_f32_e32 v2, 0x3fb8aa3b, v2
	v_exp_f32_e32 v19, v2
	v_fma_f32 v2, v18, s43, -v22
	v_mul_f32_e32 v2, 0x3fb8aa3b, v2
	v_exp_f32_e32 v18, v2
	v_fma_f32 v21, v21, s43, -v22
	v_mul_f32_e32 v21, 0x3fb8aa3b, v21
	v_add_f32_e32 v2, v19, v18
	ds_bpermute_b32 v23, v24, v2
	ds_write2st64_b32 v13, v19, v18 offset0:1 offset1:2
	s_waitcnt lgkmcnt(0)
	v_lshl_add_u64 v[18:19], v[8:9], 0, s[0:1]
	s_waitcnt lgkmcnt(1)
	v_add_f32_e32 v2, v2, v23
	ds_bpermute_b32 v23, v25, v2
	s_waitcnt lgkmcnt(0)
	v_add_f32_e32 v2, v2, v23
	ds_bpermute_b32 v23, v26, v2
	s_waitcnt lgkmcnt(0)
	v_add_f32_e32 v2, v2, v23
	ds_bpermute_b32 v23, v27, v2
	s_waitcnt lgkmcnt(0)
	v_add_f32_e32 v36, v2, v23
	ds_bpermute_b32 v37, v28, v36
	v_lshlrev_b32_e32 v2, 16, v35
	v_exp_f32_e32 v23, v21
	s_waitcnt lgkmcnt(0)
	v_add_f32_e32 v35, v36, v37
	ds_bpermute_b32 v36, v29, v35
	v_mul_f32_e32 v21, v23, v2
	v_lshrrev_b32_e32 v184, 4, v0
	v_and_b32_e32 v185, 15, v0
	v_lshlrev_b32_e32 v186, 10, v184
	v_lshl_add_u32 v186, v185, 4, v186
	v_lshlrev_b32_e32 v188, 2, v0
	v_sub_u32_e32 v186, v186, v188
	v_mov_b32_e32 v187, 0
	v_lshl_add_u64 v[182:183], v[18:19], 0, v[186:187]
	s_mov_b32 s0, 0xffff8400
	s_mov_b32 s1, -1
	v_lshl_add_u64 v[182:183], v[182:183], 0, s[0:1]
	v_lshl_add_u32 v189, v184, 2, s23
	v_add_u32_e32 v189, 0x20b00, v189
	v_mov_b32_e32 v178, 0
	v_mov_b32_e32 v179, 0
	v_mov_b32_e32 v180, 0
	v_mov_b32_e32 v181, 0
	s_mov_b32 s0, 0x1000
	s_mov_b32 s1, 0
	global_load_dwordx4 v[38:41], v[182:183], off
	v_lshl_add_u64 v[182:183], v[182:183], 0, s[0:1]
	global_load_dwordx4 v[42:45], v[182:183], off
	v_lshl_add_u64 v[182:183], v[182:183], 0, s[0:1]
	global_load_dwordx4 v[46:49], v[182:183], off
	v_lshl_add_u64 v[182:183], v[182:183], 0, s[0:1]
	global_load_dwordx4 v[50:53], v[182:183], off
	v_lshl_add_u64 v[182:183], v[182:183], 0, s[0:1]
	global_load_dwordx4 v[54:57], v[182:183], off
	v_lshl_add_u64 v[182:183], v[182:183], 0, s[0:1]
	global_load_dwordx4 v[58:61], v[182:183], off
	v_lshl_add_u64 v[182:183], v[182:183], 0, s[0:1]
	global_load_dwordx4 v[62:65], v[182:183], off
	v_lshl_add_u64 v[182:183], v[182:183], 0, s[0:1]
	global_load_dwordx4 v[66:69], v[182:183], off
	v_lshl_add_u64 v[182:183], v[182:183], 0, s[0:1]
	global_load_dwordx4 v[70:73], v[182:183], off
	v_lshl_add_u64 v[182:183], v[182:183], 0, s[0:1]
	global_load_dwordx4 v[74:77], v[182:183], off
	v_lshl_add_u64 v[182:183], v[182:183], 0, s[0:1]
	global_load_dwordx4 v[78:81], v[182:183], off
	v_lshl_add_u64 v[182:183], v[182:183], 0, s[0:1]
	global_load_dwordx4 v[82:85], v[182:183], off
	v_lshl_add_u64 v[182:183], v[182:183], 0, s[0:1]
	global_load_dwordx4 v[86:89], v[182:183], off
	v_lshl_add_u64 v[182:183], v[182:183], 0, s[0:1]
	global_load_dwordx4 v[90:93], v[182:183], off
	v_lshl_add_u64 v[182:183], v[182:183], 0, s[0:1]
	global_load_dwordx4 v[94:97], v[182:183], off
	v_lshl_add_u64 v[182:183], v[182:183], 0, s[0:1]
	global_load_dwordx4 v[200:203], v[182:183], off
	v_lshl_add_u64 v[182:183], v[182:183], 0, s[0:1]
	ds_read_b32 v162, v189
	ds_read_b32 v163, v189 offset:16
	ds_read_b32 v164, v189 offset:32
	ds_read_b32 v165, v189 offset:48
	ds_read_b32 v166, v189 offset:64
	ds_read_b32 v167, v189 offset:80
	ds_read_b32 v168, v189 offset:96
	ds_read_b32 v169, v189 offset:112
	ds_read_b32 v170, v189 offset:128
	ds_read_b32 v171, v189 offset:144
	ds_read_b32 v172, v189 offset:160
	ds_read_b32 v173, v189 offset:176
	ds_read_b32 v174, v189 offset:192
	ds_read_b32 v175, v189 offset:208
	ds_read_b32 v176, v189 offset:224
	ds_read_b32 v177, v189 offset:240
	s_waitcnt lgkmcnt(0)
	s_waitcnt vmcnt(15)
	v_fmac_f32_e32 v178, v162, v38
	v_fmac_f32_e32 v179, v162, v39
	v_fmac_f32_e32 v180, v162, v40
	v_fmac_f32_e32 v181, v162, v41
	s_waitcnt vmcnt(14)
	v_fmac_f32_e32 v178, v163, v42
	v_fmac_f32_e32 v179, v163, v43
	v_fmac_f32_e32 v180, v163, v44
	v_fmac_f32_e32 v181, v163, v45
	s_waitcnt vmcnt(13)
	v_fmac_f32_e32 v178, v164, v46
	v_fmac_f32_e32 v179, v164, v47
	v_fmac_f32_e32 v180, v164, v48
	v_fmac_f32_e32 v181, v164, v49
	s_waitcnt vmcnt(12)
	v_fmac_f32_e32 v178, v165, v50
	v_fmac_f32_e32 v179, v165, v51
	v_fmac_f32_e32 v180, v165, v52
	v_fmac_f32_e32 v181, v165, v53
	s_waitcnt vmcnt(11)
	v_fmac_f32_e32 v178, v166, v54
	v_fmac_f32_e32 v179, v166, v55
	v_fmac_f32_e32 v180, v166, v56
	v_fmac_f32_e32 v181, v166, v57
	s_waitcnt vmcnt(10)
	v_fmac_f32_e32 v178, v167, v58
	v_fmac_f32_e32 v179, v167, v59
	v_fmac_f32_e32 v180, v167, v60
	v_fmac_f32_e32 v181, v167, v61
	s_waitcnt vmcnt(9)
	v_fmac_f32_e32 v178, v168, v62
	v_fmac_f32_e32 v179, v168, v63
	v_fmac_f32_e32 v180, v168, v64
	v_fmac_f32_e32 v181, v168, v65
	s_waitcnt vmcnt(8)
	v_fmac_f32_e32 v178, v169, v66
	v_fmac_f32_e32 v179, v169, v67
	v_fmac_f32_e32 v180, v169, v68
	v_fmac_f32_e32 v181, v169, v69
	s_waitcnt vmcnt(7)
	v_fmac_f32_e32 v178, v170, v70
	v_fmac_f32_e32 v179, v170, v71
	v_fmac_f32_e32 v180, v170, v72
	v_fmac_f32_e32 v181, v170, v73
	s_waitcnt vmcnt(6)
	v_fmac_f32_e32 v178, v171, v74
	v_fmac_f32_e32 v179, v171, v75
	v_fmac_f32_e32 v180, v171, v76
	v_fmac_f32_e32 v181, v171, v77
	s_waitcnt vmcnt(5)
	v_fmac_f32_e32 v178, v172, v78
	v_fmac_f32_e32 v179, v172, v79
	v_fmac_f32_e32 v180, v172, v80
	v_fmac_f32_e32 v181, v172, v81
	s_waitcnt vmcnt(4)
	v_fmac_f32_e32 v178, v173, v82
	v_fmac_f32_e32 v179, v173, v83
	v_fmac_f32_e32 v180, v173, v84
	v_fmac_f32_e32 v181, v173, v85
	s_waitcnt vmcnt(3)
	v_fmac_f32_e32 v178, v174, v86
	v_fmac_f32_e32 v179, v174, v87
	v_fmac_f32_e32 v180, v174, v88
	v_fmac_f32_e32 v181, v174, v89
	s_waitcnt vmcnt(2)
	v_fmac_f32_e32 v178, v175, v90
	v_fmac_f32_e32 v179, v175, v91
	v_fmac_f32_e32 v180, v175, v92
	v_fmac_f32_e32 v181, v175, v93
	s_waitcnt vmcnt(1)
	v_fmac_f32_e32 v178, v176, v94
	v_fmac_f32_e32 v179, v176, v95
	v_fmac_f32_e32 v180, v176, v96
	v_fmac_f32_e32 v181, v176, v97
	s_waitcnt vmcnt(0)
	v_fmac_f32_e32 v178, v177, v200
	v_fmac_f32_e32 v179, v177, v201
	v_fmac_f32_e32 v180, v177, v202
	v_fmac_f32_e32 v181, v177, v203
	global_load_dwordx4 v[38:41], v[182:183], off
	v_lshl_add_u64 v[182:183], v[182:183], 0, s[0:1]
	global_load_dwordx4 v[42:45], v[182:183], off
	v_lshl_add_u64 v[182:183], v[182:183], 0, s[0:1]
	global_load_dwordx4 v[46:49], v[182:183], off
	v_lshl_add_u64 v[182:183], v[182:183], 0, s[0:1]
	global_load_dwordx4 v[50:53], v[182:183], off
	v_lshl_add_u64 v[182:183], v[182:183], 0, s[0:1]
	global_load_dwordx4 v[54:57], v[182:183], off
	v_lshl_add_u64 v[182:183], v[182:183], 0, s[0:1]
	global_load_dwordx4 v[58:61], v[182:183], off
	v_lshl_add_u64 v[182:183], v[182:183], 0, s[0:1]
	global_load_dwordx4 v[62:65], v[182:183], off
	v_lshl_add_u64 v[182:183], v[182:183], 0, s[0:1]
	global_load_dwordx4 v[66:69], v[182:183], off
	v_lshl_add_u64 v[182:183], v[182:183], 0, s[0:1]
	global_load_dwordx4 v[70:73], v[182:183], off
	v_lshl_add_u64 v[182:183], v[182:183], 0, s[0:1]
	global_load_dwordx4 v[74:77], v[182:183], off
	v_lshl_add_u64 v[182:183], v[182:183], 0, s[0:1]
	global_load_dwordx4 v[78:81], v[182:183], off
	v_lshl_add_u64 v[182:183], v[182:183], 0, s[0:1]
	global_load_dwordx4 v[82:85], v[182:183], off
	v_lshl_add_u64 v[182:183], v[182:183], 0, s[0:1]
	global_load_dwordx4 v[86:89], v[182:183], off
	v_lshl_add_u64 v[182:183], v[182:183], 0, s[0:1]
	global_load_dwordx4 v[90:93], v[182:183], off
	v_lshl_add_u64 v[182:183], v[182:183], 0, s[0:1]
	global_load_dwordx4 v[94:97], v[182:183], off
	v_lshl_add_u64 v[182:183], v[182:183], 0, s[0:1]
	global_load_dwordx4 v[200:203], v[182:183], off
	v_lshl_add_u64 v[182:183], v[182:183], 0, s[0:1]
	ds_read_b32 v162, v189 offset:256
	ds_read_b32 v163, v189 offset:272
	ds_read_b32 v164, v189 offset:288
	ds_read_b32 v165, v189 offset:304
	ds_read_b32 v166, v189 offset:320
	ds_read_b32 v167, v189 offset:336
	ds_read_b32 v168, v189 offset:352
	ds_read_b32 v169, v189 offset:368
	ds_read_b32 v170, v189 offset:384
	ds_read_b32 v171, v189 offset:400
	ds_read_b32 v172, v189 offset:416
	ds_read_b32 v173, v189 offset:432
	ds_read_b32 v174, v189 offset:448
	ds_read_b32 v175, v189 offset:464
	ds_read_b32 v176, v189 offset:480
	ds_read_b32 v177, v189 offset:496
	s_waitcnt lgkmcnt(0)
	s_waitcnt vmcnt(15)
	v_fmac_f32_e32 v178, v162, v38
	v_fmac_f32_e32 v179, v162, v39
	v_fmac_f32_e32 v180, v162, v40
	v_fmac_f32_e32 v181, v162, v41
	s_waitcnt vmcnt(14)
	v_fmac_f32_e32 v178, v163, v42
	v_fmac_f32_e32 v179, v163, v43
	v_fmac_f32_e32 v180, v163, v44
	v_fmac_f32_e32 v181, v163, v45
	s_waitcnt vmcnt(13)
	v_fmac_f32_e32 v178, v164, v46
	v_fmac_f32_e32 v179, v164, v47
	v_fmac_f32_e32 v180, v164, v48
	v_fmac_f32_e32 v181, v164, v49
	s_waitcnt vmcnt(12)
	v_fmac_f32_e32 v178, v165, v50
	v_fmac_f32_e32 v179, v165, v51
	v_fmac_f32_e32 v180, v165, v52
	v_fmac_f32_e32 v181, v165, v53
	s_waitcnt vmcnt(11)
	v_fmac_f32_e32 v178, v166, v54
	v_fmac_f32_e32 v179, v166, v55
	v_fmac_f32_e32 v180, v166, v56
	v_fmac_f32_e32 v181, v166, v57
	s_waitcnt vmcnt(10)
	v_fmac_f32_e32 v178, v167, v58
	v_fmac_f32_e32 v179, v167, v59
	v_fmac_f32_e32 v180, v167, v60
	v_fmac_f32_e32 v181, v167, v61
	s_waitcnt vmcnt(9)
	v_fmac_f32_e32 v178, v168, v62
	v_fmac_f32_e32 v179, v168, v63
	v_fmac_f32_e32 v180, v168, v64
	v_fmac_f32_e32 v181, v168, v65
	s_waitcnt vmcnt(8)
	v_fmac_f32_e32 v178, v169, v66
	v_fmac_f32_e32 v179, v169, v67
	v_fmac_f32_e32 v180, v169, v68
	v_fmac_f32_e32 v181, v169, v69
	s_waitcnt vmcnt(7)
	v_fmac_f32_e32 v178, v170, v70
	v_fmac_f32_e32 v179, v170, v71
	v_fmac_f32_e32 v180, v170, v72
	v_fmac_f32_e32 v181, v170, v73
	s_waitcnt vmcnt(6)
	v_fmac_f32_e32 v178, v171, v74
	v_fmac_f32_e32 v179, v171, v75
	v_fmac_f32_e32 v180, v171, v76
	v_fmac_f32_e32 v181, v171, v77
	s_waitcnt vmcnt(5)
	v_fmac_f32_e32 v178, v172, v78
	v_fmac_f32_e32 v179, v172, v79
	v_fmac_f32_e32 v180, v172, v80
	v_fmac_f32_e32 v181, v172, v81
	s_waitcnt vmcnt(4)
	v_fmac_f32_e32 v178, v173, v82
	v_fmac_f32_e32 v179, v173, v83
	v_fmac_f32_e32 v180, v173, v84
	v_fmac_f32_e32 v181, v173, v85
	s_waitcnt vmcnt(3)
	v_fmac_f32_e32 v178, v174, v86
	v_fmac_f32_e32 v179, v174, v87
	v_fmac_f32_e32 v180, v174, v88
	v_fmac_f32_e32 v181, v174, v89
	s_waitcnt vmcnt(2)
	v_fmac_f32_e32 v178, v175, v90
	v_fmac_f32_e32 v179, v175, v91
	v_fmac_f32_e32 v180, v175, v92
	v_fmac_f32_e32 v181, v175, v93
	s_waitcnt vmcnt(1)
	v_fmac_f32_e32 v178, v176, v94
	v_fmac_f32_e32 v179, v176, v95
	v_fmac_f32_e32 v180, v176, v96
	v_fmac_f32_e32 v181, v176, v97
	s_waitcnt vmcnt(0)
	v_fmac_f32_e32 v178, v177, v200
	v_fmac_f32_e32 v179, v177, v201
	v_fmac_f32_e32 v180, v177, v202
	v_fmac_f32_e32 v181, v177, v203
	ds_bpermute_b32 v190, v28, v178
	ds_bpermute_b32 v191, v28, v179
	ds_bpermute_b32 v192, v28, v180
	ds_bpermute_b32 v193, v28, v181
	s_waitcnt lgkmcnt(0)
	v_add_f32_e32 v178, v178, v190
	v_add_f32_e32 v179, v179, v191
	v_add_f32_e32 v180, v180, v192
	v_add_f32_e32 v181, v181, v193
	ds_bpermute_b32 v190, v29, v178
	ds_bpermute_b32 v191, v29, v179
	ds_bpermute_b32 v192, v29, v180
	ds_bpermute_b32 v193, v29, v181
	s_waitcnt lgkmcnt(0)
	v_add_f32_e32 v178, v178, v190
	v_add_f32_e32 v179, v179, v191
	v_add_f32_e32 v180, v180, v192
	v_add_f32_e32 v181, v181, v193
	v_lshrrev_b32_e32 v194, 2, v0
	v_lshlrev_b32_e32 v194, 2, v194
	v_and_b32_e32 v199, 3, v0
	ds_bpermute_b32 v195, v194, v178
	ds_bpermute_b32 v196, v194, v179
	ds_bpermute_b32 v197, v194, v180
	ds_bpermute_b32 v198, v194, v181
	s_waitcnt lgkmcnt(0)
	v_cmp_eq_u32_e32 vcc, 1, v199
	s_nop 1
	v_cndmask_b32_e32 v195, v195, v196, vcc
	v_cmp_eq_u32_e32 vcc, 2, v199
	s_nop 1
	v_cndmask_b32_e32 v195, v195, v197, vcc
	v_cmp_eq_u32_e32 vcc, 3, v199
	s_nop 1
	v_cndmask_b32_e32 v195, v195, v198, vcc
	v_add_f32_e32 v21, v21, v195
	s_mov_b32 s19, 0
	v_add_co_u32_e32 v14, vcc, s30, v14
	global_load_ushort v16, v[16:17], off offset:3072
	s_nop 0
	v_addc_co_u32_e32 v15, vcc, 0, v15, vcc
	global_load_ushort v14, v[14:15], off offset:1024
	v_lshlrev_b32_e32 v11, 16, v11
	v_sub_f32_e32 v15, v20, v22
	v_mul_f32_e32 v18, 0x3d372713, v11
	v_mul_f32_e32 v15, 0x3fb8aa3b, v15
	v_mul_f32_e32 v18, v18, v11
	v_exp_f32_e32 v15, v15
	v_fma_f32 v18, v18, v11, v11
	v_add_f32_e32 v17, v35, v36
	v_mul_f32_e32 v18, 0x3f4c422a, v18
	v_add_f32_e32 v17, v23, v17
	v_add_f32_e32 v18, v18, v18
	v_mul_f32_e32 v18, 0xbfb8aa3b, v18
	v_add_f32_e32 v15, v15, v17
	s_lshl_b64 s[0:1], s[16:17], 11
	v_exp_f32_e32 v17, v18
	v_div_scale_f32 v18, s[16:17], v15, v15, v21
	v_rcp_f32_e32 v19, v18
	v_add_f32_e32 v17, 1.0, v17
	v_div_scale_f32 v20, vcc, v21, v15, v21
	v_fma_f32 v22, -v18, v19, 1.0
	v_rcp_f32_e32 v17, v17
	v_fmac_f32_e32 v19, v22, v19
	v_mul_f32_e32 v22, v20, v19
	v_fma_f32 v23, -v18, v22, v20
	v_fmac_f32_e32 v22, v23, v19
	v_mul_f32_e32 v11, v17, v11
	v_fma_f32 v17, -v18, v22, v20
	v_mul_f32_e32 v11, v11, v34
	v_div_fmas_f32 v17, v17, v19, v22
	v_div_fixup_f32 v15, v17, v15, v21
	s_add_u32 s0, s25, s0
	s_addc_u32 s1, s26, s1
	v_lshlrev_b32_e32 v12, 1, v12
	s_and_b64 vcc, exec, s[4:5]
	s_waitcnt vmcnt(1)
	v_lshlrev_b32_e32 v16, 16, v16
	v_mul_f32_e32 v16, 0xbfb8aa3b, v16
	v_exp_f32_e32 v16, v16
	s_waitcnt vmcnt(0)
	v_lshlrev_b32_e32 v14, 16, v14
	v_mul_f32_e32 v14, 0xbfb8aa3b, v14
	v_exp_f32_e32 v14, v14
	v_add_f32_e32 v16, 1.0, v16
	v_rcp_f32_e32 v16, v16
	v_add_f32_e32 v14, 1.0, v14
	v_rcp_f32_e32 v14, v14
	s_nop 0
	v_mul_f32_e32 v11, v11, v14
	v_fmac_f32_e32 v11, v15, v16
	v_cvt_pk_bf16_f32 v11, v11, s0
	global_store_short v12, v11, s[0:1]
	s_waitcnt lgkmcnt(0)
	s_cbranch_vccz .LBB0_287
	s_or_b32 s0, s18, 0x7f
	s_ashr_i32 s1, s0, 31
	s_lshl_b64 s[0:1], s[0:1], 10
	s_add_u32 s0, s80, s0
	s_addc_u32 s1, s81, s1
	s_add_u32 s0, s0, s2
	s_addc_u32 s1, s1, 0
	v_mov_b32_e32 v11, v3
	v_lshl_add_u64 v[14:15], s[0:1], 0, v[10:11]
	v_add_co_u32_e32 v16, vcc, 0x84c0000, v14
	s_nop 1
	v_addc_co_u32_e32 v17, vcc, 0, v15, vcc
	v_add_co_u32_e32 v14, vcc, 0x94c0000, v14
	global_store_dword v[16:17], v1, off
	s_nop 0
	v_addc_co_u32_e32 v15, vcc, 0, v15, vcc
	global_store_dword v[14:15], v2, off
	s_branch .LBB0_287
